# v38 + next tile's V pieces issued before its K pieces in the diff loop heads
# baseline (speedup 1.0000x reference)
; template <int DQK>
; __device__ __forceinline__ void attn_pass4(LAS unsigned char* lds, const bf16* Qp, int qpitch, const bf16* Kp, int kpitch, const bf16* Vp, int vpitch, int q0, f32x16 (&o)[4], float (&rl)[16]) {
;     ...
;         for (int t = 0; t < NT; ++t) {
;             const int vnext = ATT_VNEXT(vcur);
;             if (t + 1 < NT) ATT_DMA(t + 1, (t + 1) & 1, vnext);
.LBB0_621:
	s_add_i32 s25, s24, 1
	s_cmp_lg_u32 s24, 2
	s_cselect_b32 s35, s25, 0
	s_add_i32 s25, s72, 1
	s_cmp_ge_u32 s25, s31
	s_cbranch_scc1 .LBB0_625
	s_mul_i32 s73, s35, 0x5000
	s_add_i32 s73, s26, s73
	s_mov_b32 m0, s73
	s_add_u32 s74, s70, 0x4000000
	s_addc_u32 s75, s71, 0
	global_load_lds_dwordx4 v172, s[74:75]
	s_add_i32 m0, s73, 0x2000
	v_readfirstlane_b32 s32, v242
	global_load_lds_dwordx4 v174, s[74:75]
	s_cmpk_gt_u32 s32, 0xff
	s_cbranch_scc1 .Lskip_v2_0
	s_add_i32 m0, s73, 0x4000
	v_lshl_add_u64 v[114:115], s[74:75], 0, v[178:179]
	global_load_lds_dwordx4 v[114:115], off
.Lskip_v2_0:
	s_bitcmp1_b32 s25, 0
	s_cselect_b32 s73, 0x2400, 0
	s_add_i32 m0, s73, s5
	s_andn2_b64 vcc, exec, s[10:11]
	global_load_lds_dwordx4 v170, s[70:71]
	s_cbranch_vccnz .LBB0_624
	s_add_i32 m0, s73, s80
	s_nop 0
	global_load_lds_dwordx4 v176, s[70:71]

; template <int DQK>
; __device__ __forceinline__ void attn_pass4(LAS unsigned char* lds, const bf16* Qp, int qpitch, const bf16* Kp, int kpitch, const bf16* Vp, int vpitch, int q0, f32x16 (&o)[4], float (&rl)[16]) {
;     ...
;         for (int t = 0; t < NT; ++t) {
;             const int vnext = ATT_VNEXT(vcur);
;             if (t + 1 < NT) ATT_DMA(t + 1, (t + 1) & 1, vnext);
.LBB0_821:
	s_add_i32 s24, s35, 1
	s_cmp_lg_u32 s35, 2
	s_cselect_b32 s24, s24, 0
	s_add_i32 s25, s72, 1
	s_cmp_ge_u32 s25, s31
	s_cbranch_scc1 .LBB0_825
	s_mul_i32 s73, s24, 0x5000
	s_add_i32 s73, s5, s73
	s_mov_b32 m0, s73
	s_add_u32 s74, s70, 0x3ffff80
	s_addc_u32 s75, s71, 0
	global_load_lds_dwordx4 v172, s[74:75]
	s_add_i32 m0, s73, 0x2000
	v_readfirstlane_b32 s32, v242
	global_load_lds_dwordx4 v174, s[74:75]
	s_cmpk_gt_u32 s32, 0xff
	s_cbranch_scc1 .Lskip_v2_1
	s_add_i32 m0, s73, 0x4000
	v_lshl_add_u64 v[114:115], s[74:75], 0, v[178:179]
	global_load_lds_dwordx4 v[114:115], off
.Lskip_v2_1:
	s_bitcmp1_b32 s25, 0
	s_cselect_b32 s73, 0x2400, 0
	s_add_i32 m0, s73, s3
	s_andn2_b64 vcc, exec, s[10:11]
	global_load_lds_dwordx4 v170, s[70:71]
	s_cbranch_vccnz .LBB0_824
	s_add_i32 m0, s73, s27
	s_nop 0
	global_load_lds_dwordx4 v176, s[70:71]
